# moba pairing re-optimised after the scan got faster, with a convex item-cost model fitted to measured per-class idle times: scan-class and the group holding workgroup 128 take (9,4)/(11,2)/(8,6), prep
# baseline (speedup 1.0000x reference)
.LBB0_565:
	s_cbranch_execz .LBB0_643
	s_lshl_b32 s0, s76, 2
	s_and_b32 s73, s0, 28
	s_lshl_b32 s0, s76, 11
	s_ashr_i32 s33, s76, 3
	s_lshr_b32 s98, s33, 3
	s_lshl_b32 s98, s98, 2
	s_lshr_b32 s98, 0xacdfe624, s98
	s_and_b32 s98, s98, 15
	s_sub_i32 s98, 15, s98
	s_lshl_b32 s98, s98, 3
	s_and_b32 s33, s33, 7
	s_or_b32 s33, s33, s98
	s_and_b32 s52, s0, 0x3000
	s_ashr_i32 s2, s42, 3
	s_not_b32 s72, s33
	s_or_b32 s74, s52, 64
	s_add_u32 s66, s58, 0x2cd1000
	s_addc_u32 s67, s59, 0
	s_add_u32 s75, s58, 0x8cd1000
	s_addc_u32 s77, s59, 0
	s_add_u32 s78, s58, 0xbd0000
	v_mbcnt_lo_u32_b32 v0, -1, 0
	s_addc_u32 s79, s59, 0
	v_mbcnt_hi_u32_b32 v196, -1, v0
	s_mov_b32 s63, 0
	s_add_u32 s68, s58, 0xcd1000
	v_and_b32_e32 v0, 64, v196
	s_mov_b32 s53, s63
	s_addc_u32 s69, s59, 0
	v_mov_b32_e32 v33, 0
	s_movk_i32 s80, 0xff
	s_movk_i32 s81, 0x1800
	s_mov_b32 s82, 0xefa18f08
	v_xor_b32_e32 v197, 32, v196
	v_add_u32_e32 v198, 64, v0
	v_mov_b32_e32 v199, 0xff800000
	v_mov_b32_e32 v200, 0x3f803f80
	s_mov_b32 s6, 0
	s_mov_b32 s83, 0
	v_readlane_b32 s98, v255, 14
	s_nop 3
	s_cmp_lg_u32 s98, 0
	s_cbranch_scc1 .Lmoba_dq_latch2
	s_branch .LBB0_569

.Lmoba_dq_latch2:
	s_waitcnt lgkmcnt(0)
	s_barrier
	v_readlane_b32 s98, v255, 19
	s_nop 3
	s_cmp_lg_u32 s98, 0
	s_cbranch_scc1 .LBB0_643
	s_mov_b32 s98, 1
	s_nop 0
	v_writelane_b32 v255, s98, 19
	s_ashr_i32 s14, s76, 3
	s_lshr_b32 s0, s14, 3
	s_lshl_b32 s0, s0, 2
	s_lshr_b32 s0, 0x753108b9, s0
	s_and_b32 s0, s0, 15
	s_sub_i32 s0, 15, s0
	s_lshl_b32 s0, s0, 3
	s_and_b32 s14, s14, 7
	s_or_b32 s14, s14, s0
	s_branch .LBB0_574
